# phase H: latch reuses the precomputed next tile id (no gridDim reload), later tiles skip the redundant second prologue barrier
# speedup vs baseline: 1.0019x; 1.0019x over previous
; DI uint2 pk4(float a, float b, float c, float d) { uint2 o; o.x = pk2(a, b); o.y = pk2(c, d); return o; }
; DI void phaseH(int wv0, PP p, unsigned char* smem) {
;     ...
;   for (int id = blockIdx.x; id < 128 * 16; id += gridDim.x) {
;     int pm, pn;
;     tile_map_n16(id, pm, pn);
;     const int brow = pm * 256, bcol = pn * 256;
;     const int tid = my_tid(wv0);
;     if (tid < 256) {
;       const float4* s = (const float4*)(SS1 + (size_t)(brow + tid) * 16);
;       const float4 a = s[0], b = s[1], c = s[2], d = s[3];
;       const float t = a.x + a.y + a.z + a.w + b.x + b.y + b.z + b.w + c.x + c.y + c.z + c.w + d.x + d.y + d.z + d.w;
;       sR[tid] = rsqrtf(t * (1.f / 1024.f) + 1e-6f);
;     }
;     f32x4 acc[2][2][4][2];
;     gemm256(wv0, acc, X1B + (size_t)brow * 1024, 1024, (const u16*)(p->ws + OFF_WUPT) + (size_t)bcol * 1024, 1024, 1024, smem);
;     epi256(wv0, acc, brow, bcol, [&](int ai, int bj, int m, int n, int row, int col0, f32x4& v) {
;       const float ri = sR[row - brow];
;       const float a0 = fmaxf(v[0] * ri, 0.f), a1 = fmaxf(v[1] * ri, 0.f), a2 = fmaxf(v[2] * ri, 0.f), a3 = fmaxf(v[3] * ri, 0.f);
;       *(uint2*)(ACT + (size_t)row * 4096 + col0) = pk4(a0 * a0, a1 * a1, a2 * a2, a3 * a3);
;     });
;     __syncthreads();
;   }
.Lmy_hn_nowr:
	s_waitcnt lgkmcnt(0)
	s_barrier
	s_mov_b32 s67, s88
	s_cmpk_lt_i32 s67, 0x800
	s_cbranch_scc0 .Lmy_hn_exit

; DI void gemm256(int wv0, f32x4 (&acc)[2][2][4][2], const u16* __restrict__ A, int lda, const u16* __restrict__ Bt, int ldb,
;                 int K, unsigned char* smem) {
;   u16* shm = (u16*)smem;
;   const int tid = my_tid(wv0), lane = tid & 63;
;   const int wr = wv0 >> 2, wc = wv0 & 3, fr = lane & 15, fq = lane >> 4;
;     ...
;   int sr0, sc0, sr1, sc1;
;   stage_rc(tid * 16, sr0, sc0);
;   stage_rc(tid * 16 + 8192, sr1, sc1);
;   const u16* a0 = A + (size_t)sr0 * lda + sc0;
;   const u16* a1 = A + (size_t)sr1 * lda + sc1;
;   const u16* b0 = Bt + (size_t)sr0 * ldb + sc0;
;   const u16* b1 = Bt + (size_t)sr1 * ldb + sc1;
; DI void phaseH(int wv0, PP p, unsigned char* smem) {
;     ...
;     const int tid = my_tid(wv0);
;     if (tid < 256) {
;       const float4* s = (const float4*)(SS1 + (size_t)(brow + tid) * 16);
;       const float4 a = s[0], b = s[1], c = s[2], d = s[3];
;       const float t = a.x + a.y + a.z + a.w + b.x + b.y + b.z + b.w + c.x + c.y + c.z + c.w + d.x + d.y + d.z + d.w;
;       sR[tid] = rsqrtf(t * (1.f / 1024.f) + 1e-6f);
;     }
.LBB0_1136:
	v_mov_b32_e32 v12, v142
	s_lshl_b32 s4, s67, 3
	v_bfe_i32 v1, v12, 27, 1
	v_lshlrev_b32_e32 v13, 4, v12
	v_lshrrev_b32_e32 v1, 22, v1
	v_add_u32_e32 v1, v13, v1
	v_and_b32_e32 v1, 0xfffffc00, v1
	v_ashrrev_i32_e32 v0, 31, v12
	v_sub_u32_e32 v1, v13, v1
	v_lshrrev_b32_e32 v0, 26, v0
	v_lshrrev_b32_e32 v2, 4, v1
	v_add_u32_e32 v0, v12, v0
	v_bitop3_b32 v2, v2, v1, 32 bitop3:0x6c
	v_ashrrev_i32_e32 v1, 31, v1
	v_ashrrev_i32_e32 v0, 6, v0
	v_lshrrev_b32_e32 v1, 26, v1
	v_lshlrev_b32_e32 v3, 3, v0
	v_add_u32_e32 v1, v2, v1
	v_and_b32_e32 v3, -16, v3
	v_ashrrev_i32_e32 v1, 6, v1
	v_add_u32_e32 v4, v1, v3
	v_mul_i32_i24_e32 v1, 64, v1
	v_lshlrev_b32_e32 v0, 5, v0
	v_sub_u32_e32 v1, v2, v1
	v_and_b32_e32 v0, 32, v0
	v_ashrrev_i16_sdwa v1, v144, sext(v1) dst_sel:DWORD dst_unused:UNUSED_PAD src0_sel:DWORD src1_sel:BYTE_0
	v_add_u32_sdwa v0, v0, sext(v1) dst_sel:DWORD dst_unused:UNUSED_PAD src0_sel:DWORD src1_sel:WORD_0
	v_add_u32_e32 v1, 0x2000, v13
	v_ashrrev_i32_e32 v2, 31, v1
	v_lshrrev_b32_e32 v2, 22, v2
	v_add_u32_e32 v2, v1, v2
	v_ashrrev_i32_e32 v2, 10, v2
	v_mul_i32_i24_e32 v3, 0x400, v2
	v_sub_u32_e32 v1, v1, v3
	v_lshrrev_b32_e32 v3, 4, v1
	v_bitop3_b32 v1, v3, v1, 32 bitop3:0x6c
	s_and_b32 s47, s4, 8
	s_bfe_u32 s4, s67, 0x30003
	v_ashrrev_i32_e32 v5, 31, v1
	s_or_b32 s48, s47, s4
	s_ashr_i32 s47, s46, 31
	v_lshrrev_b32_e32 v5, 26, v5
	s_lshl_b64 s[72:73], s[46:47], 11
	v_lshlrev_b32_e32 v3, 3, v2
	v_add_u32_e32 v5, v1, v5
	s_add_u32 s72, s0, s72
	v_and_b32_e32 v3, -16, v3
	v_ashrrev_i32_e32 v6, 6, v5
	s_addc_u32 s73, s1, s73
	s_lshl_b32 s47, s48, 19
	v_add_u32_e32 v8, v6, v3
	v_and_b32_e32 v3, 0xc0, v5
	s_add_u32 s74, s33, s47
	v_lshlrev_b32_e32 v2, 5, v2
	v_sub_u32_e32 v1, v1, v3
	s_addc_u32 s75, s50, 0
	v_and_b32_e32 v2, 32, v2
	v_ashrrev_i16_sdwa v1, v144, sext(v1) dst_sel:DWORD dst_unused:UNUSED_PAD src0_sel:DWORD src1_sel:BYTE_0
	v_ashrrev_i32_e32 v5, 31, v4
	s_add_i32 s47, 32, 0x10000
	v_add_u32_sdwa v2, v2, sext(v1) dst_sel:DWORD dst_unused:UNUSED_PAD src0_sel:DWORD src1_sel:WORD_0
	v_ashrrev_i32_e32 v1, 31, v0
	v_ashrrev_i32_e32 v9, 31, v8
	v_lshlrev_b64 v[6:7], 11, v[4:5]
	v_add_u32_e32 v148, s47, v13
	v_ashrrev_i32_e32 v3, 31, v2
	v_lshl_add_u64 v[10:11], s[74:75], 0, v[6:7]
	v_lshlrev_b64 v[4:5], 11, v[8:9]
	v_lshlrev_b64 v[16:17], 1, v[0:1]
	v_readfirstlane_b32 s47, v148
	v_add_u32_e32 v149, 0x2000, v148
	v_lshl_add_u64 v[8:9], s[74:75], 0, v[4:5]
	v_lshlrev_b64 v[18:19], 1, v[2:3]
	v_lshl_add_u64 v[10:11], v[10:11], 0, v[16:17]
	s_mov_b32 m0, s47
	v_readfirstlane_b32 s47, v149
	v_add_u32_e32 v150, 32, v13
	v_lshl_add_u64 v[14:15], s[72:73], 0, v[6:7]
	v_lshl_add_u64 v[8:9], v[8:9], 0, v[18:19]
	s_cmp_lg_u32 s80, 0
	s_cbranch_scc1 .Lmy_hn_pro_skip
	s_waitcnt vmcnt(0)
	s_waitcnt vmcnt(0) lgkmcnt(0)
	v_and_b32_e32 v184, 0xff, v142
	v_lshl_add_u32 v184, v184, 2, 32
	v_add_u32_e32 v184, 0x213e0, v184
	v_add_f32_e32 v185, v168, v169
	v_add_f32_e32 v185, v185, v170
	v_add_f32_e32 v185, v185, v171
	v_add_f32_e32 v185, v185, v172
	v_add_f32_e32 v185, v185, v173
	v_add_f32_e32 v185, v185, v174
	v_add_f32_e32 v185, v185, v175
	v_add_f32_e32 v185, v185, v176
	v_add_f32_e32 v185, v185, v177
	v_add_f32_e32 v185, v185, v178
	v_add_f32_e32 v185, v185, v179
	v_add_f32_e32 v185, v185, v180
	v_add_f32_e32 v185, v185, v181
	v_add_f32_e32 v185, v185, v182
	v_add_f32_e32 v185, v185, v183
	v_fmamk_f32 v185, v185, 0x3a800000, v143
	v_mul_f32_e32 v186, 0x4b800000, v185
	v_cmp_gt_f32_e32 vcc, s66, v185
	s_nop 1
	v_cndmask_b32_e32 v185, v185, v186, vcc
	v_rsq_f32_e32 v185, v185
	s_nop 0
	v_mul_f32_e32 v186, 0x45800000, v185
	v_cndmask_b32_e32 v185, v185, v186, vcc
	ds_write_b32 v184, v185
	s_barrier
	s_branch .Lmy_hn_pro_done

; #define WAIT_V(n) asm volatile("s_waitcnt vmcnt(" #n ")" ::: "memory")
; #define BAR __builtin_amdgcn_s_barrier()
; DI void gemm256(int wv0, f32x4 (&acc)[2][2][4][2], const u16* __restrict__ A, int lda, const u16* __restrict__ Bt, int ldb,
;                 int K, unsigned char* smem) {
;     ...
;   WAIT_V(0);
;   __syncthreads();
;   STAGE_B(SB(0, 0), 0, 0) STAGE_A(SA(0, 0), 0, 0)
;   STAGE_B(SB(0, 1), 1, 0) STAGE_A(SA(0, 1), 1, 0)
;   if (wr == 1) BAR;
.Lmy_hn_pro_done:
	global_load_lds_dwordx4 v[10:11], off
	s_mov_b32 m0, s47
	v_readfirstlane_b32 s47, v150
	v_add_u32_e32 v151, 0x2000, v150
	v_lshl_add_u64 v[132:133], v[14:15], 0, v[16:17]
	global_load_lds_dwordx4 v[8:9], off
	s_mov_b32 m0, s47
	v_readfirstlane_b32 s47, v151
	global_load_lds_dwordx4 v[132:133], off
	s_mov_b32 m0, s47
	s_add_i32 s47, 32, 0x14000
	v_lshl_add_u64 v[14:15], s[72:73], 0, v[4:5]
	v_add_u32_e32 v152, s47, v13
	v_lshl_add_u64 v[130:131], v[14:15], 0, v[18:19]
	v_readfirstlane_b32 s47, v152
	v_add_u32_e32 v153, 0x2000, v152
	global_load_lds_dwordx4 v[130:131], off
	v_lshl_add_u64 v[14:15], v[10:11], 0, s[18:19]
	s_mov_b32 m0, s47
	v_readfirstlane_b32 s47, v153
	v_add_u32_e32 v154, 0x4000, v150
	global_load_lds_dwordx4 v[14:15], off
	v_lshl_add_u64 v[14:15], v[8:9], 0, s[18:19]
	s_mov_b32 m0, s47
	v_readfirstlane_b32 s47, v154
	v_add_u32_e32 v155, 0x6000, v150
	global_load_lds_dwordx4 v[14:15], off
	v_lshl_add_u64 v[14:15], v[132:133], 0, s[18:19]
	s_mov_b32 m0, s47
	v_readfirstlane_b32 s47, v155
	global_load_lds_dwordx4 v[14:15], off
	v_lshl_add_u64 v[14:15], v[130:131], 0, s[18:19]
	s_mov_b32 m0, s47
	s_andn2_b64 vcc, exec, s[12:13]
	global_load_lds_dwordx4 v[14:15], off
	s_cbranch_vccnz .LBB0_1138
	s_barrier
